# next layer W_in/Wq/Wkv transposes also moved behind the attention queue of layer 0 (W_out transpose stays in the RMSNorm phase)
# baseline (speedup 1.0000x reference)
.Lxp0_end:
	s_cmp_lt_u32 s2, 64
	s_cbranch_scc1 .Lx2_end
	s_load_dwordx2 s[10:11], s[0:1], 0xe0
	v_mov_b32_e32 v30, v152
	v_and_b32_e32 v29, 63, v30
	v_lshlrev_b32_e32 v20, 3, v29
	v_readfirstlane_b32 s4, v30
	s_ashr_i32 s21, s4, 6
	s_sub_u32 s4, s2, 64
	s_lshl_b32 s4, s4, 3
	s_add_i32 s18, s4, s21
	s_sub_u32 s20, s38, 64
	s_lshl_b32 s19, s20, 3
	s_mov_b32 s8, s0
	s_mov_b32 s9, s1
	s_waitcnt lgkmcnt(0)
	s_cmpk_gt_i32 s18, 0x61f
	s_cbranch_scc1 .Lx2_end
	s_load_dwordx4 s[4:7], s[8:9], 0x18
	s_load_dwordx4 s[24:27], s[8:9], 0xa8
	s_lshl_b32 s8, s21, 14
	v_lshrrev_b32_e32 v18, 5, v29
	v_lshlrev_b32_e32 v0, 2, v30
	s_add_i32 s8, s8, 0
	v_and_b32_e32 v0, 0x7c, v0
	v_mul_u32_u24_e32 v4, 0x84, v18
	v_mov_b32_e32 v1, 0
	v_add3_u32 v19, s8, v0, v4
	v_and_b32_e32 v4, 56, v20
	s_waitcnt lgkmcnt(0)
	v_lshl_add_u64 v[2:3], s[6:7], 0, v[0:1]
	s_mov_b64 s[6:7], 0x400000
	v_lshrrev_b32_e32 v21, 3, v29
	v_mul_u32_u24_e32 v6, 0x84, v4
	v_lshlrev_b32_e32 v4, 1, v4
	v_mov_b32_e32 v5, v1
	v_lshl_add_u64 v[2:3], v[2:3], 0, s[6:7]
	s_waitcnt vmcnt(0)
	v_lshl_add_u64 v[16:17], s[10:11], 0, v[4:5]
	s_mov_b64 s[6:7], 0x1290000
	v_lshlrev_b32_e32 v7, 2, v21
	v_lshl_add_u64 v[4:5], v[16:17], 0, s[6:7]
	v_add3_u32 v20, s8, v6, v7
	v_lshl_add_u64 v[6:7], s[26:27], 0, v[0:1]
	s_mov_b64 s[6:7], 0x100000
	v_lshl_add_u64 v[6:7], v[6:7], 0, s[6:7]
	s_mov_b64 s[6:7], 0x1210000
	v_lshl_add_u64 v[8:9], v[16:17], 0, s[6:7]
	v_lshl_add_u64 v[10:11], s[24:25], 0, v[0:1]
	s_mov_b64 s[6:7], 0x120000
	v_lshl_add_u64 v[14:15], s[4:5], 0, v[0:1]
	s_mov_b64 s[4:5], 0xa20000
	v_lshl_add_u64 v[10:11], v[10:11], 0, s[6:7]
	s_mov_b64 s[6:7], 0x1180000
	v_lshl_add_u64 v[14:15], v[14:15], 0, s[4:5]
	s_mov_b64 s[4:5], 0xc00000
	v_lshl_add_u64 v[12:13], v[16:17], 0, s[6:7]
	v_lshl_add_u64 v[16:17], v[16:17], 0, s[4:5]
	s_lshl_b32 s4, s18, 1
	s_mov_b32 s9, 0
	v_or_b32_e32 v22, 8, v21
	v_or_b32_e32 v23, 16, v21
	v_or_b32_e32 v24, 24, v21
	s_lshl_b32 s6, s18, 5
	s_lshl_b32 s7, s20, 8
	s_add_i32 s10, s4, 0x1f3c0
	s_lshl_b32 s11, s20, 4
	s_movk_i32 s14, 0x4000
	s_movk_i32 s15, 0x6000
	s_mov_b32 s16, 0xa000
	s_mov_b32 s17, 0xc000
	s_mov_b32 s20, 0x10000
	s_mov_b32 s21, 0x12000
	s_mov_b32 s22, 0x16000
	s_mov_b32 s23, 0x18000
	s_mov_b32 s24, 0x1c000
	s_mov_b32 s25, 0x1e000
	s_mov_b32 s26, 0x22000
	s_mov_b32 s27, 0x24000
	s_mov_b32 s28, 0x28000
	s_mov_b32 s29, 0x2a000
	s_mov_b32 s30, 0x2e000
	s_movk_i32 s31, 0x1000
	s_movk_i32 s34, 0x3000
	s_movk_i32 s35, 0x7000
	s_mov_b32 s36, 0x9000
	s_mov_b32 s37, 0xd000
	s_mov_b32 s42, 0xf000
	s_mov_b32 s43, 0x13000
	s_mov_b32 s44, 0x15000
	s_mov_b32 s45, 0x19000
	s_mov_b32 s46, 0x1b000
	s_mov_b32 s47, 0x1f000
	s_mov_b32 s48, 0x21000
	s_mov_b32 s49, 0x25000
	s_mov_b32 s50, 0x27000
	s_mov_b32 s51, 0x2b000
	s_mov_b32 s52, 0x2d000
	s_movk_i32 s53, 0x2880
	v_add_u32_e32 v25, 0x400, v19
	v_add_u32_e32 v26, 0x800, v19
	v_add_u32_e32 v27, 0xc00, v19
	v_add_u32_e32 v28, 0x1000, v19
	v_add_u32_e32 v29, 0x1400, v19
	v_add_u32_e32 v30, 0x1800, v19
	v_add_u32_e32 v31, 0x1c00, v19
	s_branch .Lx2_733
.Lx2_732:
	s_add_i32 s18, s18, s19
	s_add_i32 s6, s6, s7
	s_add_i32 s10, s10, s11
	s_cmpk_lt_i32 s18, 0x620
	s_cbranch_scc0 .Lx2_end

.LBB0_730:
	s_addk_i32 s18, 0x620
	s_cmpk_gt_i32 s18, 0x81f
	s_cbranch_scc1 .LBB0_745
	s_load_dwordx4 s[4:7], s[8:9], 0x18
	s_load_dwordx4 s[24:27], s[8:9], 0xa8
	s_lshl_b32 s8, s21, 14
	v_lshrrev_b32_e32 v18, 5, v29
	v_lshlrev_b32_e32 v0, 2, v30
	s_add_i32 s8, s8, 0
	v_and_b32_e32 v0, 0x7c, v0
	v_mul_u32_u24_e32 v4, 0x84, v18
	v_mov_b32_e32 v1, 0
	v_add3_u32 v19, s8, v0, v4
	v_and_b32_e32 v4, 56, v20
	s_waitcnt lgkmcnt(0)
	v_lshl_add_u64 v[2:3], s[6:7], 0, v[0:1]
	s_mov_b64 s[6:7], 0x400000
	v_lshrrev_b32_e32 v21, 3, v29
	v_mul_u32_u24_e32 v6, 0x84, v4
	v_lshlrev_b32_e32 v4, 1, v4
	v_mov_b32_e32 v5, v1
	v_lshl_add_u64 v[2:3], v[2:3], 0, s[6:7]
	s_waitcnt vmcnt(0)
	v_lshl_add_u64 v[16:17], s[10:11], 0, v[4:5]
	s_mov_b64 s[6:7], 0x1290000
	v_lshlrev_b32_e32 v7, 2, v21
	v_lshl_add_u64 v[4:5], v[16:17], 0, s[6:7]
	v_add3_u32 v20, s8, v6, v7
	v_lshl_add_u64 v[6:7], s[26:27], 0, v[0:1]
	s_mov_b64 s[6:7], 0x100000
	v_lshl_add_u64 v[6:7], v[6:7], 0, s[6:7]
	s_mov_b64 s[6:7], 0x1210000
	v_lshl_add_u64 v[8:9], v[16:17], 0, s[6:7]
	v_lshl_add_u64 v[10:11], s[24:25], 0, v[0:1]
	s_mov_b64 s[6:7], 0x120000
	v_lshl_add_u64 v[14:15], s[4:5], 0, v[0:1]
	s_mov_b64 s[4:5], 0xa20000
	v_lshl_add_u64 v[10:11], v[10:11], 0, s[6:7]
	s_mov_b64 s[6:7], 0x1180000
	v_lshl_add_u64 v[14:15], v[14:15], 0, s[4:5]
	s_mov_b64 s[4:5], 0xc00000
	v_lshl_add_u64 v[12:13], v[16:17], 0, s[6:7]
	v_lshl_add_u64 v[16:17], v[16:17], 0, s[4:5]
	s_lshl_b32 s4, s18, 1
	s_mov_b32 s9, 0
	v_or_b32_e32 v22, 8, v21
	v_or_b32_e32 v23, 16, v21
	v_or_b32_e32 v24, 24, v21
	s_lshl_b32 s6, s18, 5
	s_lshl_b32 s7, s20, 8
	s_add_i32 s10, s4, 0x1f3c0
	s_lshl_b32 s11, s20, 4
	s_movk_i32 s14, 0x4000
	s_movk_i32 s15, 0x6000
	s_mov_b32 s16, 0xa000
	s_mov_b32 s17, 0xc000
	s_mov_b32 s20, 0x10000
	s_mov_b32 s21, 0x12000
	s_mov_b32 s22, 0x16000
	s_mov_b32 s23, 0x18000
	s_mov_b32 s24, 0x1c000
	s_mov_b32 s25, 0x1e000
	s_mov_b32 s26, 0x22000
	s_mov_b32 s27, 0x24000
	s_mov_b32 s28, 0x28000
	s_mov_b32 s29, 0x2a000
	s_mov_b32 s30, 0x2e000
	s_movk_i32 s31, 0x1000
	s_movk_i32 s34, 0x3000
	s_movk_i32 s35, 0x7000
	s_mov_b32 s36, 0x9000
	s_mov_b32 s37, 0xd000
	s_mov_b32 s42, 0xf000
	s_mov_b32 s43, 0x13000
	s_mov_b32 s44, 0x15000
	s_mov_b32 s45, 0x19000
	s_mov_b32 s46, 0x1b000
	s_mov_b32 s47, 0x1f000
	s_mov_b32 s48, 0x21000
	s_mov_b32 s49, 0x25000
	s_mov_b32 s50, 0x27000
	s_mov_b32 s51, 0x2b000
	s_mov_b32 s52, 0x2d000
	s_movk_i32 s53, 0x2880
	v_add_u32_e32 v25, 0x400, v19
	v_add_u32_e32 v26, 0x800, v19
	v_add_u32_e32 v27, 0xc00, v19
	v_add_u32_e32 v28, 0x1000, v19
	v_add_u32_e32 v29, 0x1400, v19
	v_add_u32_e32 v30, 0x1800, v19
	v_add_u32_e32 v31, 0x1c00, v19
	s_branch .LBB0_733
